# pp_v28 + IDX: next unit's 12 prologue operand loads issued before the score-store drain of the current unit (land under that wait)
# speedup vs baseline: 1.0152x; 1.0035x over previous
.LBB0_572:
	s_lshl_b32 s42, s33, 5
	s_add_u32 s2, s34, s42
	s_addc_u32 s14, s35, 0
	s_cmp_lg_u32 s58, 0
	s_cbranch_scc1 .Lix_have
	v_mov_b32_e32 v3, s14
	v_or_b32_e32 v2, s2, v114
	v_lshlrev_b64 v[2:3], 10, v[2:3]
	v_lshl_add_u64 v[2:3], v[116:117], 0, v[2:3]
	global_load_dwordx4 v[66:69], v[2:3], off
	global_load_dwordx4 v[70:73], v[2:3], off offset:32
	global_load_dwordx4 v[74:77], v[2:3], off offset:64
	global_load_dwordx4 v[78:81], v[2:3], off offset:96
	v_mov_b32_e32 v3, s14
	v_or_b32_e32 v2, s2, v118
	v_lshlrev_b64 v[2:3], 5, v[2:3]
	v_lshl_add_u64 v[4:5], s[18:19], 0, v[2:3]
	global_load_dwordx4 v[82:85], v[4:5], off offset:16
	global_load_dwordx4 v[86:89], v[4:5], off
	v_or_b32_e32 v2, 32, v2
	v_lshl_add_u64 v[2:3], s[18:19], 0, v[2:3]
	global_load_dwordx4 v[98:101], v[120:121], off
	global_load_dwordx4 v[102:105], v[122:123], off
	global_load_dwordx4 v[106:109], v[124:125], off
	global_load_dwordx4 v[110:113], v[126:127], off
	global_load_dwordx4 v[90:93], v[2:3], off offset:16
	global_load_dwordx4 v[94:97], v[2:3], off
	s_branch .Lix_join
.Lix_have:
	v_mov_b64_e32 v[66:67], v[194:195]
	v_mov_b64_e32 v[68:69], v[196:197]
.Lix_join:
	s_waitcnt lgkmcnt(0)
	s_barrier
	s_cmp_gt_u32 s33, 7
	s_waitcnt vmcnt(5)
	ds_write_b128 v160, v[98:101]
	s_waitcnt vmcnt(4)
	ds_write_b128 v160, v[102:105] offset:8192
	s_waitcnt vmcnt(3)
	ds_write_b128 v160, v[106:109] offset:16384
	s_waitcnt vmcnt(2)
	ds_write_b128 v160, v[110:113] offset:24576
	s_cbranch_scc0 .LBB0_574
	global_load_dwordx4 v[98:101], v[134:135], off
	global_load_dwordx4 v[102:105], v[132:133], off
	global_load_dwordx4 v[106:109], v[130:131], off
	global_load_dwordx4 v[110:113], v[128:129], off

.LBB0_579:
	s_cmp_eq_u32 s58, 3
	s_cbranch_scc1 .Lix_nopf
	s_cmp_eq_u32 s58, 0
	s_cselect_b32 s64, s36, s37
	s_cmp_eq_u32 s58, 2
	s_cselect_b32 s64, s38, s64
	s_lshl_b32 s65, s64, 5
	s_add_u32 s66, s34, s65
	s_addc_u32 s67, s35, 0
	v_mov_b32_e32 v151, s67
	v_or_b32_e32 v150, s66, v114
	v_lshlrev_b64 v[150:151], 10, v[150:151]
	v_lshl_add_u64 v[150:151], v[116:117], 0, v[150:151]
	global_load_dwordx4 v[194:197], v[150:151], off
	global_load_dwordx4 v[70:73], v[150:151], off offset:32
	global_load_dwordx4 v[74:77], v[150:151], off offset:64
	global_load_dwordx4 v[78:81], v[150:151], off offset:96
	v_mov_b32_e32 v153, s67
	v_or_b32_e32 v152, s66, v118
	v_lshlrev_b64 v[152:153], 5, v[152:153]
	v_lshl_add_u64 v[154:155], s[18:19], 0, v[152:153]
	global_load_dwordx4 v[82:85], v[154:155], off offset:16
	global_load_dwordx4 v[86:89], v[154:155], off
	v_or_b32_e32 v152, 32, v152
	v_lshl_add_u64 v[152:153], s[18:19], 0, v[152:153]
	global_load_dwordx4 v[98:101], v[120:121], off
	global_load_dwordx4 v[102:105], v[122:123], off
	global_load_dwordx4 v[106:109], v[124:125], off
	global_load_dwordx4 v[110:113], v[126:127], off
	global_load_dwordx4 v[90:93], v[152:153], off offset:16
	global_load_dwordx4 v[94:97], v[152:153], off
